# P0 x->bf16 conversion loop unrolled by four (16 loads in flight per thread, store acks no longer serialise each trip)
# baseline (speedup 1.0000x reference)
; DEVINL void phase0(const Params& p) {
;     ...
;     for (long i = (long)bid * 512 + tid; i < n4; i += 4 * stride) {
;       const f32x4* xq = (const f32x4*)xs;
;       const f32x4 q0 = __builtin_nontemporal_load(xq + i), q1 = __builtin_nontemporal_load(xq + i + stride);
;       const f32x4 q2 = __builtin_nontemporal_load(xq + i + 2 * stride), q3 = __builtin_nontemporal_load(xq + i + 3 * stride);
;       float4 v0 = make_float4(q0[0], q0[1], q0[2], q0[3]), v1 = make_float4(q1[0], q1[1], q1[2], q1[3]);
;       float4 v2 = make_float4(q2[0], q2[1], q2[2], q2[3]), v3 = make_float4(q3[0], q3[1], q3[2], q3[3]);
;       xd[i] = make_uint2(pk2(v0.x, v0.y), pk2(v0.z, v0.w));
;       xd[i + stride] = make_uint2(pk2(v1.x, v1.y), pk2(v1.z, v1.w));
;       xd[i + 2 * stride] = make_uint2(pk2(v2.x, v2.y), pk2(v2.z, v2.w));
;       xd[i + 3 * stride] = make_uint2(pk2(v3.x, v3.y), pk2(v3.z, v3.w));
;     }
.LBB0_19:
	global_load_dwordx4 v[6:9], v[2:3], off nt
	v_lshl_add_u64 v[10:11], v[2:3], 0, s[8:9]
	v_lshl_add_u64 v[14:15], v[2:3], 0, s[14:15]
	v_lshl_add_u64 v[18:19], v[2:3], 0, s[16:17]
	global_load_dwordx4 v[10:13], v[10:11], off nt
	s_nop 0
	global_load_dwordx4 v[14:17], v[14:15], off nt
	s_nop 0
	global_load_dwordx4 v[18:21], v[18:19], off nt
	v_lshl_add_u64 v[0:1], v[0:1], 0, s[6:7]
	v_lshl_add_u64 v[22:23], v[4:5], 0, s[10:11]
	v_cmp_lt_i64_e32 vcc, s[20:21], v[0:1]
	v_lshl_add_u64 v[24:25], v[22:23], 0, s[10:11]
	v_lshl_add_u64 v[2:3], v[2:3], 0, s[12:13]
	s_or_b64 s[18:19], vcc, s[18:19]
	v_lshl_add_u64 v[26:27], v[24:25], 0, s[10:11]
	v_mov_b32_e32 v28, v4
	v_mov_b32_e32 v29, v5
	v_lshl_add_u64 v[4:5], v[4:5], 0, s[14:15]
	global_load_dwordx4 v[58:61], v[2:3], off nt
	v_lshl_add_u64 v[62:63], v[2:3], 0, s[8:9]
	v_lshl_add_u64 v[66:67], v[2:3], 0, s[14:15]
	v_lshl_add_u64 v[70:71], v[2:3], 0, s[16:17]
	global_load_dwordx4 v[62:65], v[62:63], off nt
	s_nop 0
	global_load_dwordx4 v[66:69], v[66:67], off nt
	s_nop 0
	global_load_dwordx4 v[70:73], v[70:71], off nt
	v_lshl_add_u64 v[0:1], v[0:1], 0, s[6:7]
	v_lshl_add_u64 v[74:75], v[4:5], 0, s[10:11]
	v_cmp_lt_i64_e32 vcc, s[20:21], v[0:1]
	v_lshl_add_u64 v[76:77], v[74:75], 0, s[10:11]
	v_lshl_add_u64 v[2:3], v[2:3], 0, s[12:13]
	s_or_b64 s[18:19], vcc, s[18:19]
	v_lshl_add_u64 v[78:79], v[76:77], 0, s[10:11]
	v_mov_b32_e32 v80, v4
	v_mov_b32_e32 v81, v5
	v_lshl_add_u64 v[4:5], v[4:5], 0, s[14:15]
	global_load_dwordx4 v[110:113], v[2:3], off nt
	v_lshl_add_u64 v[114:115], v[2:3], 0, s[8:9]
	v_lshl_add_u64 v[118:119], v[2:3], 0, s[14:15]
	v_lshl_add_u64 v[122:123], v[2:3], 0, s[16:17]
	global_load_dwordx4 v[114:117], v[114:115], off nt
	s_nop 0
	global_load_dwordx4 v[118:121], v[118:119], off nt
	s_nop 0
	global_load_dwordx4 v[122:125], v[122:123], off nt
	v_lshl_add_u64 v[0:1], v[0:1], 0, s[6:7]
	v_lshl_add_u64 v[126:127], v[4:5], 0, s[10:11]
	v_cmp_lt_i64_e32 vcc, s[20:21], v[0:1]
	v_lshl_add_u64 v[128:129], v[126:127], 0, s[10:11]
	v_lshl_add_u64 v[2:3], v[2:3], 0, s[12:13]
	s_or_b64 s[18:19], vcc, s[18:19]
	v_lshl_add_u64 v[130:131], v[128:129], 0, s[10:11]
	v_mov_b32_e32 v132, v4
	v_mov_b32_e32 v133, v5
	v_lshl_add_u64 v[4:5], v[4:5], 0, s[14:15]
	global_load_dwordx4 v[206:209], v[2:3], off nt
	v_lshl_add_u64 v[210:211], v[2:3], 0, s[8:9]
	v_lshl_add_u64 v[214:215], v[2:3], 0, s[14:15]
	v_lshl_add_u64 v[218:219], v[2:3], 0, s[16:17]
	global_load_dwordx4 v[210:213], v[210:211], off nt
	s_nop 0
	global_load_dwordx4 v[214:217], v[214:215], off nt
	s_nop 0
	global_load_dwordx4 v[218:221], v[218:219], off nt
	v_lshl_add_u64 v[0:1], v[0:1], 0, s[6:7]
	v_lshl_add_u64 v[222:223], v[4:5], 0, s[10:11]
	v_cmp_lt_i64_e32 vcc, s[20:21], v[0:1]
	v_lshl_add_u64 v[224:225], v[222:223], 0, s[10:11]
	v_lshl_add_u64 v[2:3], v[2:3], 0, s[12:13]
	s_or_b64 s[18:19], vcc, s[18:19]
	v_lshl_add_u64 v[226:227], v[224:225], 0, s[10:11]
	v_mov_b32_e32 v228, v4
	v_mov_b32_e32 v229, v5
	v_lshl_add_u64 v[4:5], v[4:5], 0, s[14:15]
	s_waitcnt vmcnt(15)
	v_cvt_pk_bf16_f32 v6, v6, v7
	v_cvt_pk_bf16_f32 v7, v8, v9
	global_store_dwordx2 v[28:29], v[6:7], off
	s_waitcnt vmcnt(15)
	v_cvt_pk_bf16_f32 v6, v10, v11
	v_cvt_pk_bf16_f32 v7, v12, v13
	s_waitcnt vmcnt(14)
	v_cvt_pk_bf16_f32 v8, v14, v15
	v_cvt_pk_bf16_f32 v9, v16, v17
	s_waitcnt vmcnt(13)
	v_cvt_pk_bf16_f32 v10, v18, v19
	v_cvt_pk_bf16_f32 v11, v20, v21
	global_store_dwordx2 v[22:23], v[6:7], off
	global_store_dwordx2 v[24:25], v[8:9], off
	global_store_dwordx2 v[26:27], v[10:11], off
	s_waitcnt vmcnt(15)
	v_cvt_pk_bf16_f32 v58, v58, v59
	v_cvt_pk_bf16_f32 v59, v60, v61
	global_store_dwordx2 v[80:81], v[58:59], off
	s_waitcnt vmcnt(15)
	v_cvt_pk_bf16_f32 v58, v62, v63
	v_cvt_pk_bf16_f32 v59, v64, v65
	s_waitcnt vmcnt(14)
	v_cvt_pk_bf16_f32 v60, v66, v67
	v_cvt_pk_bf16_f32 v61, v68, v69
	s_waitcnt vmcnt(13)
	v_cvt_pk_bf16_f32 v62, v70, v71
	v_cvt_pk_bf16_f32 v63, v72, v73
	global_store_dwordx2 v[74:75], v[58:59], off
	global_store_dwordx2 v[76:77], v[60:61], off
	global_store_dwordx2 v[78:79], v[62:63], off
	s_waitcnt vmcnt(15)
	v_cvt_pk_bf16_f32 v110, v110, v111
	v_cvt_pk_bf16_f32 v111, v112, v113
	global_store_dwordx2 v[132:133], v[110:111], off
	s_waitcnt vmcnt(15)
	v_cvt_pk_bf16_f32 v110, v114, v115
	v_cvt_pk_bf16_f32 v111, v116, v117
	s_waitcnt vmcnt(14)
	v_cvt_pk_bf16_f32 v112, v118, v119
	v_cvt_pk_bf16_f32 v113, v120, v121
	s_waitcnt vmcnt(13)
	v_cvt_pk_bf16_f32 v114, v122, v123
	v_cvt_pk_bf16_f32 v115, v124, v125
	global_store_dwordx2 v[126:127], v[110:111], off
	global_store_dwordx2 v[128:129], v[112:113], off
	global_store_dwordx2 v[130:131], v[114:115], off
	s_waitcnt vmcnt(15)
	v_cvt_pk_bf16_f32 v206, v206, v207
	v_cvt_pk_bf16_f32 v207, v208, v209
	global_store_dwordx2 v[228:229], v[206:207], off
	s_waitcnt vmcnt(15)
	v_cvt_pk_bf16_f32 v206, v210, v211
	v_cvt_pk_bf16_f32 v207, v212, v213
	s_waitcnt vmcnt(14)
	v_cvt_pk_bf16_f32 v208, v214, v215
	v_cvt_pk_bf16_f32 v209, v216, v217
	s_waitcnt vmcnt(13)
	v_cvt_pk_bf16_f32 v210, v218, v219
	v_cvt_pk_bf16_f32 v211, v220, v221
	global_store_dwordx2 v[222:223], v[206:207], off
	global_store_dwordx2 v[224:225], v[208:209], off
	global_store_dwordx2 v[226:227], v[210:211], off
	s_andn2_b64 exec, exec, s[18:19]
	s_cbranch_execnz .LBB0_19
